# prep: element-wise items moved off the adaLN GEMV blocks (blocks 192..511, stride 320)
# baseline (speedup 1.0000x reference)
; __device__ __forceinline__ int bid_() { int b = blockIdx.x; asm volatile("" : "+s"(b)); return b; }
; __device__ __forceinline__ void phase_prep(const Params& p, unsigned char* smem) {
;   const int G = gridDim.x;
;   int t = bid_();
;   for (; t < 192; t += G) ada_item(p, t, smem);
;   t -= 192;
;   for (; t < 128; t += G) fold_item(p, t, smem);
;   t -= 128;
;   for (; t < 13440; t += G) conv_item(p, t, smem);
;   t -= 13440;
;   for (; t < 2336; t += G) elem_item(p, t);
.LBB0_23:
	s_add_i32 s14, s2, 0x33c0
	s_cmp_lt_u32 s2, 0xc0
	s_cselect_b32 s14, 0x7fff, s14
	s_cmp_lt_u32 s2, 0x140
	s_cbranch_scc1 .LBB0_62
	s_sub_i32 s14, s2, 0x140
	s_load_dwordx2 s[0:1], s[64:65], 0x1b0
	s_lshl_b32 s15, s14, 6
	s_lshl_b32 s17, s14, 4
	s_lshl_b32 s19, s14, 5
	s_lshl_b32 s21, s14, 2
	s_waitcnt lgkmcnt(0)
	s_mov_b64 s[4:5], s[0:1]
	s_movk_i32 s4, 0xc0
	s_lshl_b32 s0, s14, 3
	s_lshl_b32 s16, s4, 6
	s_lshl_b32 s18, s4, 4
	s_lshl_b32 s20, s4, 5
	s_lshl_b32 s22, s4, 2
	s_add_i32 s23, s0, 0xffff6e00
	s_lshl_b32 s24, s4, 3
	s_mov_b32 s5, 0
	v_mov_b32_e32 v19, 0
	s_mov_b32 s25, 0x10000
	s_mov_b32 s26, 0x20000
	s_mov_b32 s27, 0x30000
	s_movk_i32 s28, 0x104
	s_movk_i32 s29, 0x90
	s_mov_b32 s30, 0x8000
	s_mov_b32 s31, 0x18000
	s_movk_i32 s33, 0xc00
	s_movk_i32 s34, 0x1300
	v_mov_b32_e32 v1, 0xc0000
	v_mov_b32_e32 v25, 0x60000
	v_mov_b32_e32 v27, 0x4c0000
	v_mov_b32_e32 v28, 0x300000
	s_branch .LBB0_26

; __device__ __forceinline__ u16 f2bf(float f) { return (u16)(pack2(f, 0.f) & 0xffffu); }
; __device__ __forceinline__ int tid_() { int t = threadIdx.x; asm volatile("" : "+v"(t)); return t; }
; __device__ __forceinline__ void convT_tile(const float* __restrict__ src, int lds, int k0, int c0, u16* __restrict__ dst, int Kd,
;                                            int rbase, int mode, int which, unsigned char* smem, const float* __restrict__ kscale = nullptr) {
;   float* tile = (float*)smem;
;   const int t = tid_();
;   float4 v4[4];
; #pragma unroll
;   for (int i = 0; i < 4; ++i) {
;     const f32x4 w_ = __builtin_nontemporal_load((const f32x4*)(src + (size_t)(k0 + i * 16 + (t >> 4)) * lds + c0 + (t & 15) * 4));
;     v4[i] = make_float4(w_[0], w_[1], w_[2], w_[3]);
;   }
; #pragma unroll
;   for (int i = 0; i < 4; ++i) {
;     const int kk = i * 16 + (t >> 4), cc = (t & 15) * 4;
;     const float sc = kscale ? kscale[k0 + kk] : 1.f;
;     tile[kk * 65 + cc + 0] = v4[i].x * sc; tile[kk * 65 + cc + 1] = v4[i].y * sc;
;     tile[kk * 65 + cc + 2] = v4[i].z * sc; tile[kk * 65 + cc + 3] = v4[i].w * sc;
;   }
;   __syncthreads();
; #pragma unroll
;   for (int i = 0; i < 16; ++i) {
;     const int cc = i * 4 + (t >> 6), kk = t & 63;
;     int row;
;     if (mode == 0) row = rbase + cc;
;     else { const int f = c0 + cc; row = (((f >> 4) * 2 + which) << 4) + (f & 15); }
;     dst[(size_t)row * Kd + k0 + kk] = f2bf(tile[kk * 65 + cc]);
;   }
;   __syncthreads();
; }
; __device__ __forceinline__ void conv_item(const Params& p, int it, unsigned char* smem) {
;     ...
;   {
;     const int e = r >> 7, r3 = r & 127, ct = r3 >> 3, kt = r3 & 7;
;     convT_tile(p.w_down + (size_t)(l * 16 + e) * 512 * 1024, 1024, kt * 64, ct * 64, p.WdT + (size_t)(l * 16 + e) * 1024 * 512, 512, ct * 64, 0, 0, smem);
;   }
.Lprep_convdone:
	s_add_i32 s14, s2, 0x33c0
	s_branch .LBB0_62
	s_nop 0
	v_mov_b64_e32 v[2:3], s[10:11]
	global_load_dwordx2 v[4:5], v[2:3], off offset:160
	s_add_i32 s0, s35, 0xffffedc0
	s_lshl_b32 s1, s6, 4
	s_lshl_b32 s4, s6, 9
	s_lshr_b32 s0, s0, 7
	v_mov_b32_e32 v6, v187
	s_sub_i32 s4, s23, s4
	s_add_i32 s0, s0, s1
	global_load_dwordx2 v[2:3], v[2:3], off offset:232
	s_and_b32 s12, s4, 0x3c0
	v_ashrrev_i32_e32 v9, 6, v6
	s_ashr_i32 s1, s0, 31
	s_and_b32 s7, s15, 0x1c0
	v_ashrrev_i32_e32 v8, 4, v6
	s_lshl_b32 s4, s12, 2
	v_add_u32_e32 v16, s12, v9
	s_lshl_b64 s[12:13], s[0:1], 21
	v_lshlrev_b32_e32 v7, 4, v6
	v_and_b32_e32 v24, 63, v6
	v_add_u32_e32 v6, s7, v8
	v_and_b32_e32 v18, 0xf0, v7
	v_ashrrev_i32_e32 v7, 31, v6
	v_lshlrev_b64 v[6:7], 12, v[6:7]
	v_lshlrev_b32_e32 v9, 2, v9
	v_mad_u64_u32 v[30:31], s[36:37], v8, s28, v[18:19]
	v_mad_u32_u24 v26, v24, s28, v9
	v_add_u32_e32 v29, 0x1040, v30
	v_add_u32_e32 v31, 0x1048, v30
	v_add_u32_e32 v62, 0x2080, v30
	v_add_u32_e32 v63, 0x2088, v30
	v_add_u32_e32 v64, 0x30c0, v30
	v_add_u32_e32 v65, 0x30c8, v30
	s_lshl_b64 s[0:1], s[0:1], 20
	v_add_u32_e32 v34, 8, v16
	v_add_u32_e32 v36, 12, v16
	v_add_u32_e32 v38, 16, v16
	v_add_u32_e32 v40, 20, v16
	v_add_u32_e32 v42, 24, v16
	v_add_u32_e32 v44, 28, v16
	v_add_u32_e32 v46, 32, v16
	v_add_u32_e32 v48, 36, v16
	v_add_u32_e32 v50, 40, v16
	v_add_u32_e32 v52, 44, v16
	v_add_u32_e32 v54, 48, v16
	v_add_u32_e32 v56, 52, v16
	v_add_u32_e32 v58, 56, v16
	v_add_u32_e32 v60, 60, v16
	v_ashrrev_i32_e32 v17, 31, v16
	v_ashrrev_i32_e32 v35, 31, v34
	v_ashrrev_i32_e32 v37, 31, v36
	v_ashrrev_i32_e32 v39, 31, v38
	v_ashrrev_i32_e32 v41, 31, v40
	v_ashrrev_i32_e32 v43, 31, v42
	v_ashrrev_i32_e32 v45, 31, v44
	v_ashrrev_i32_e32 v47, 31, v46
	v_ashrrev_i32_e32 v49, 31, v48
	v_ashrrev_i32_e32 v51, 31, v50
	v_ashrrev_i32_e32 v53, 31, v52
	v_ashrrev_i32_e32 v55, 31, v54
	v_ashrrev_i32_e32 v57, 31, v56
	v_ashrrev_i32_e32 v59, 31, v58
	v_ashrrev_i32_e32 v61, 31, v60
	v_lshlrev_b64 v[34:35], 10, v[34:35]
	v_lshlrev_b64 v[36:37], 10, v[36:37]
	v_lshlrev_b64 v[38:39], 10, v[38:39]
	v_lshlrev_b64 v[40:41], 10, v[40:41]
	v_lshlrev_b64 v[42:43], 10, v[42:43]
	v_lshlrev_b64 v[44:45], 10, v[44:45]
	v_lshlrev_b64 v[46:47], 10, v[46:47]
	v_lshlrev_b64 v[48:49], 10, v[48:49]
	v_lshlrev_b64 v[50:51], 10, v[50:51]
	v_lshlrev_b64 v[52:53], 10, v[52:53]
	v_lshlrev_b64 v[54:55], 10, v[54:55]
	v_lshlrev_b64 v[56:57], 10, v[56:57]
	v_lshlrev_b64 v[58:59], 10, v[58:59]
	v_lshlrev_b64 v[60:61], 10, v[60:61]
	s_waitcnt vmcnt(0) lgkmcnt(0)
	v_lshl_add_u64 v[4:5], v[4:5], 0, s[12:13]
	v_lshl_add_u64 v[4:5], v[4:5], 0, s[4:5]
	v_lshl_add_u64 v[4:5], v[4:5], 0, v[18:19]
	v_lshl_add_u64 v[20:21], v[4:5], 0, v[6:7]
	v_add_co_u32_e32 v22, vcc, s25, v20
	s_lshl_b32 s4, s7, 1
	s_nop 0
	v_addc_co_u32_e32 v23, vcc, 0, v21, vcc
	v_add_co_u32_e32 v32, vcc, s26, v20
	v_lshl_add_u64 v[2:3], v[2:3], 0, s[0:1]
	s_nop 0
	v_addc_co_u32_e32 v33, vcc, 0, v21, vcc
	global_load_dwordx4 v[4:7], v[20:21], off nt
	global_load_dwordx4 v[8:11], v[22:23], off nt
	global_load_dwordx4 v[12:15], v[32:33], off nt
	v_add_co_u32_e32 v20, vcc, s27, v20
	v_add_u32_e32 v32, 4, v16
	s_nop 0
	v_addc_co_u32_e32 v21, vcc, 0, v21, vcc
	global_load_dwordx4 v[20:23], v[20:21], off nt
	v_ashrrev_i32_e32 v33, 31, v32
	v_lshl_add_u64 v[2:3], v[2:3], 0, s[4:5]
	v_lshlrev_b32_e32 v18, 1, v24
	v_lshlrev_b64 v[16:17], 10, v[16:17]
	v_lshlrev_b64 v[32:33], 10, v[32:33]
	v_lshl_add_u64 v[2:3], v[2:3], 0, v[18:19]
	v_lshl_add_u64 v[16:17], v[2:3], 0, v[16:17]
	v_lshl_add_u64 v[32:33], v[2:3], 0, v[32:33]
	v_lshl_add_u64 v[34:35], v[2:3], 0, v[34:35]
	v_lshl_add_u64 v[36:37], v[2:3], 0, v[36:37]
	v_lshl_add_u64 v[38:39], v[2:3], 0, v[38:39]
	v_lshl_add_u64 v[40:41], v[2:3], 0, v[40:41]
	v_lshl_add_u64 v[42:43], v[2:3], 0, v[42:43]
	v_lshl_add_u64 v[44:45], v[2:3], 0, v[44:45]
	v_lshl_add_u64 v[46:47], v[2:3], 0, v[46:47]
	v_lshl_add_u64 v[48:49], v[2:3], 0, v[48:49]
	v_lshl_add_u64 v[50:51], v[2:3], 0, v[50:51]
	v_lshl_add_u64 v[52:53], v[2:3], 0, v[52:53]
	v_lshl_add_u64 v[54:55], v[2:3], 0, v[54:55]
	v_lshl_add_u64 v[56:57], v[2:3], 0, v[56:57]
	v_lshl_add_u64 v[58:59], v[2:3], 0, v[58:59]
	v_lshl_add_u64 v[2:3], v[2:3], 0, v[60:61]
	s_waitcnt vmcnt(0) lgkmcnt(0)
	ds_write2_b32 v30, v4, v5 offset1:1
	ds_write2_b32 v30, v6, v7 offset0:2 offset1:3
	ds_write2_b32 v29, v8, v9 offset1:1
	ds_write2_b32 v31, v10, v11 offset1:1
	ds_write2_b32 v62, v12, v13 offset1:1
	ds_write2_b32 v63, v14, v15 offset1:1
	ds_write2_b32 v64, v20, v21 offset1:1
	ds_write2_b32 v65, v22, v23 offset1:1
	s_waitcnt lgkmcnt(0)
	s_barrier
	ds_read2_b32 v[4:5], v26 offset1:4
	ds_read2_b32 v[6:7], v26 offset0:8 offset1:12
	ds_read2_b32 v[8:9], v26 offset0:16 offset1:20
	ds_read2_b32 v[10:11], v26 offset0:24 offset1:28
	ds_read2_b32 v[12:13], v26 offset0:32 offset1:36
	ds_read2_b32 v[14:15], v26 offset0:40 offset1:44
	ds_read2_b32 v[20:21], v26 offset0:48 offset1:52
	ds_read2_b32 v[22:23], v26 offset0:56 offset1:60
	s_waitcnt lgkmcnt(7)
	v_cvt_pk_bf16_f32 v4, v4, s0
	v_cvt_pk_bf16_f32 v5, v5, s0
	s_waitcnt lgkmcnt(6)
	v_cvt_pk_bf16_f32 v6, v6, s0
	s_waitcnt lgkmcnt(1)
	v_cvt_pk_bf16_f32 v18, v20, s0
	v_cvt_pk_bf16_f32 v20, v21, s0
	s_waitcnt lgkmcnt(0)
	v_cvt_pk_bf16_f32 v21, v22, s0
	v_cvt_pk_bf16_f32 v22, v23, s0
	v_cvt_pk_bf16_f32 v7, v7, s0
	v_cvt_pk_bf16_f32 v8, v8, s0
	v_cvt_pk_bf16_f32 v9, v9, s0
	v_cvt_pk_bf16_f32 v10, v10, s0
	v_cvt_pk_bf16_f32 v11, v11, s0
	v_cvt_pk_bf16_f32 v12, v12, s0
	v_cvt_pk_bf16_f32 v13, v13, s0
	v_cvt_pk_bf16_f32 v14, v14, s0
	v_cvt_pk_bf16_f32 v15, v15, s0
	global_store_short v[16:17], v4, off
	global_store_short v[32:33], v5, off
	global_store_short v[34:35], v6, off
	global_store_short v[36:37], v7, off
	global_store_short v[38:39], v8, off
	global_store_short v[40:41], v9, off
	global_store_short v[42:43], v10, off
	global_store_short v[44:45], v11, off
	global_store_short v[46:47], v12, off
	global_store_short v[48:49], v13, off
	global_store_short v[50:51], v14, off
	global_store_short v[52:53], v15, off
	global_store_short v[54:55], v18, off
	global_store_short v[56:57], v20, off
	global_store_short v[58:59], v21, off
	global_store_short v[2:3], v22, off
	s_waitcnt lgkmcnt(0)
	s_barrier
	s_mov_b64 s[0:1], 0

; __device__ __forceinline__ u16 f2bf(float f) { return (u16)(pack2(f, 0.f) & 0xffffu); }
; __device__ __forceinline__ int tid_() { int t = threadIdx.x; asm volatile("" : "+v"(t)); return t; }
; __device__ __forceinline__ void elem_item(const Params& p, int it) {
;   const int t = tid_();
;   if (it < 128) {
; #pragma unroll
;     for (int i = 0; i < 4; ++i) { const int idx = it * 1024 + i * 256 + t; p.Wsgu[idx] = f2bf(p.w_sgu[idx]); }
;     return;
;   }
;   it -= 128;
; __device__ __forceinline__ void phase_prep(const Params& p, unsigned char* smem) {
;     ...
;   for (; t < 2336; t += G) elem_item(p, t);
.LBB0_62:
	s_cmpk_gt_u32 s14, 0x3d9f
	s_cbranch_scc1 .LBB0_109
	s_load_dwordx2 s[4:5], s[64:65], 0x1b0
	s_lshl_b32 s0, s14, 10
	s_add_i32 s1, s14, 0xffffcb80
	s_add_i32 s12, s0, 0xff0b8000
	s_mov_b32 s14, 0x7f800000
	s_waitcnt lgkmcnt(0)
	s_movk_i32 s4, 0x140
	s_lshl_b32 s13, s4, 10
	v_mov_b32_e32 v1, 0xbf1f24be
	v_mov_b32_e32 v6, 0x3e642e9d
	s_brev_b32 s15, 1
	s_mov_b32 s0, 0x39800000
	v_mov_b32_e32 v7, 0x7fc00000
	s_branch .LBB0_65
.LBB0_64:
	s_load_dwordx2 s[4:5], s[64:65], 0x1b0
	s_add_i32 s12, s12, s13
	s_waitcnt lgkmcnt(0)
	s_addk_i32 s1, 0x140
	s_cmpk_lt_i32 s1, 0x920
	s_cbranch_scc0 .LBB0_109
